# MLA deferred-max threshold 16 instead of 8 (reference bias 15): fewer recompute-path triggers; f32/bf16 range leaves > 100 binades of headroom
# speedup vs baseline: 1.0127x; 1.0008x over previous
; template <bool MLA> __device__ __forceinline__ void attn_unit(const AttnP& P, int b, int hh, int qb, LAS char* lds) {
;     ...
;     const int qlo = q0 + wid * 32, qm = qlo + r32 - 4 * hi;
;     bf16x8 qr[NQF];
;     const size_t qrow = rowbase + qlo + r32;
;     if constexpr (MLA) {
; #pragma unroll
;         for (int d0 = 0; d0 < 8; ++d0) qr[d0] = *(const bf16x8*)(P.QN + qrow * 2048 + hh * 128 + d0 * 16 + hi * 8);
; #pragma unroll
;         for (int d0 = 0; d0 < 4; ++d0) qr[8 + d0] = *(const bf16x8*)(P.QR + qrow * 1024 + hh * 64 + d0 * 16 + hi * 8);
;     } else {
; #pragma unroll
;         for (int d0 = 0; d0 < 4; ++d0) qr[d0] = *(const bf16x8*)(P.QS + qrow * 2048 + hh * 64 + d0 * 16 + hi * 8);
;         if (tid < 128) bias_l[tid] = P.rel[(int)T5B[tid] * 32 + hh] * (1.0f / SCALE);
;     }
;     bf16x8 sk0, sv0;
;     const int sr8 = tid >> 3, ch8 = tid & 7;
;     const bf16_t* Kg; const bf16_t* Vg; const bf16_t* Rg = nullptr;
;     unsigned okA = 0, okB = 0, orp = 0, ovA = 0, ovB = 0;
;     if constexpr (MLA) {
;         Kg = P.KN + rowbase * 2048 + hh * 128; Vg = P.V + rowbase * 2048 + hh * 128; Rg = P.KR + rowbase * 64;
;         { const int rA = 4 * wid + (lane >> 4), rB = rA + 32, cp = lane & 15; okA = (unsigned)(rA * 2048 + ((cp ^ (rA & 7)) << 3)); okB = (unsigned)(rB * 2048 + ((cp ^ (rB & 7)) << 3)); }
;         { const int rr = 8 * wid + (lane >> 3), cp = lane & 7; orp = (unsigned)(rr * 64 + ((cp ^ (rr & 7)) << 3)); }
;         { const int stA = 2 * wid + (lane >> 5), stB = stA + 16; const int kl = (lane & 31) >> 2, c8 = 8 * (lane & 3);
;           const int kkA = (stA >> 2) * 8 + kl, kkB = (stB >> 2) * 8 + kl;
;           const int kA = (kkA & ~0xC) | ((kkA & 4) << 1) | ((kkA & 8) >> 1), kB = (kkB & ~0xC) | ((kkB & 4) << 1) | ((kkB & 8) >> 1);
;           ovA = (unsigned)(kA * 2048 + 32 * (stA & 3) + c8); ovB = (unsigned)(kB * 2048 + 32 * (stB & 3) + c8); }
;     } else { Kg = P.KS + (rowbase + sr8) * 256 + (hh >> 3) * 64 + ch8 * 8; Vg = P.VS + (rowbase + sr8) * 256 + (hh >> 3) * 64 + ch8 * 8; }
;     const int kws = KSWZ64(sr8, ch8), vst0 = v_st<NCB>(sr8, ch8 * 8);
;     ...
;     float m_reg = MLA ? 0.f : P.sinks[hh] * (1.0f / SCALE), l_reg = MLA ? 0.f : 1.f;
;     f32x16 o[NCB];
; #pragma unroll
;     for (int d = 0; d < NCB; ++d) o[d] = f32x16{};
;     const int vb0 = (int)(uintptr_t)V_lds + v_rd_base(lane);
.Lm16_qb_ok:
	s_lshr_b32 s36, s28, 5
	s_and_b32 s63, s36, 15
	s_lshr_b32 s64, s36, 4
	s_lshl_b32 s40, s33, 2
	s_add_u32 s40, s40, 4
	s_lshl_b32 s43, s33, 8
	s_lshl_b32 s36, s4, 5
	s_add_u32 s43, s43, s36
	s_lshl_b32 s36, s64, 14
	s_add_u32 s36, s36, s43
	s_lshl_b32 s37, s36, 12
	s_lshl_b32 s59, s63, 8
	s_add_u32 s37, s37, s59
	s_add_u32 s66, s6, s37
	s_addc_u32 s67, s7, 0
	s_lshl_b32 s37, s36, 11
	s_lshl_b32 s59, s63, 7
	s_add_u32 s37, s37, s59
	s_add_u32 s68, s8, s37
	s_addc_u32 s69, s9, 0
	s_lshl_b32 s37, s64, 26
	s_lshl_b32 s59, s63, 8
	s_add_u32 s37, s37, s59
	s_add_u32 s46, s12, s37
	s_addc_u32 s47, s13, 0
	s_add_u32 s48, s16, s37
	s_addc_u32 s49, s17, 0
	s_lshl_b32 s37, s64, 21
	s_add_u32 s50, s14, s37
	s_addc_u32 s51, s15, 0
	global_load_dwordx4 v[66:69], v237, s[66:67] offset:0
	global_load_dwordx4 v[70:73], v237, s[66:67] offset:64
	global_load_dwordx4 v[74:77], v237, s[66:67] offset:128
	global_load_dwordx4 v[78:81], v237, s[66:67] offset:192
	global_load_dwordx4 v[82:85], v239, s[68:69] offset:0
	global_load_dwordx4 v[86:89], v239, s[68:69] offset:64
	global_load_dwordx4 v[90:93], v238, s[66:67] offset:0
	global_load_dwordx4 v[94:97], v238, s[66:67] offset:64
	global_load_dwordx4 v[98:101], v238, s[66:67] offset:128
	global_load_dwordx4 v[102:105], v238, s[66:67] offset:192
	global_load_dwordx4 v[106:109], v240, s[68:69] offset:0
	global_load_dwordx4 v[110:113], v240, s[68:69] offset:64
	s_mov_b32 s70, 0x8000
	s_mov_b32 s71, 0
	s_add_i32 s36, s5, s70
	s_mov_b32 m0, s36
	s_nop 0
	global_load_lds_dwordx4 v232, s[46:47]
	s_add_i32 m0, s36, 0x2000
	s_nop 0
	global_load_lds_dwordx4 v233, s[46:47]
	s_add_i32 m0, s36, 0x4000
	s_nop 0
	global_load_lds_dwordx4 v234, s[50:51]
	s_add_i32 s36, s5, s71
	s_mov_b32 m0, s36
	s_nop 0
	global_load_lds_dwordx4 v235, s[48:49]
	s_add_i32 m0, s36, 0x2000
	s_nop 0
	global_load_lds_dwordx4 v236, s[48:49]
	s_add_u32 s46, s46, 0x40000
	s_addc_u32 s47, s47, 0
	s_add_u32 s48, s48, 0x40000
	s_addc_u32 s49, s49, 0
	s_add_u32 s50, s50, 0x2000
	s_addc_u32 s51, s51, 0
	v_mov_b32_e32 v2, 0
	v_mov_b32_e32 v3, 0
	v_mov_b32_e32 v4, 0
	v_mov_b32_e32 v5, 0
	v_mov_b32_e32 v6, 0
	v_mov_b32_e32 v7, 0
	v_mov_b32_e32 v8, 0
	v_mov_b32_e32 v9, 0
	v_mov_b32_e32 v10, 0
	v_mov_b32_e32 v11, 0
	v_mov_b32_e32 v12, 0
	v_mov_b32_e32 v13, 0
	v_mov_b32_e32 v14, 0
	v_mov_b32_e32 v15, 0
	v_mov_b32_e32 v16, 0
	v_mov_b32_e32 v17, 0
	v_mov_b32_e32 v18, 0
	v_mov_b32_e32 v19, 0
	v_mov_b32_e32 v20, 0
	v_mov_b32_e32 v21, 0
	v_mov_b32_e32 v22, 0
	v_mov_b32_e32 v23, 0
	v_mov_b32_e32 v24, 0
	v_mov_b32_e32 v25, 0
	v_mov_b32_e32 v26, 0
	v_mov_b32_e32 v27, 0
	v_mov_b32_e32 v28, 0
	v_mov_b32_e32 v29, 0
	v_mov_b32_e32 v30, 0
	v_mov_b32_e32 v31, 0
	v_mov_b32_e32 v32, 0
	v_mov_b32_e32 v33, 0
	v_mov_b32_e32 v34, 0
	v_mov_b32_e32 v35, 0
	v_mov_b32_e32 v36, 0
	v_mov_b32_e32 v37, 0
	v_mov_b32_e32 v38, 0
	v_mov_b32_e32 v39, 0
	v_mov_b32_e32 v40, 0
	v_mov_b32_e32 v41, 0
	v_mov_b32_e32 v42, 0
	v_mov_b32_e32 v43, 0
	v_mov_b32_e32 v44, 0
	v_mov_b32_e32 v45, 0
	v_mov_b32_e32 v46, 0
	v_mov_b32_e32 v47, 0
	v_mov_b32_e32 v48, 0
	v_mov_b32_e32 v49, 0
	v_mov_b32_e32 v50, 0
	v_mov_b32_e32 v51, 0
	v_mov_b32_e32 v52, 0
	v_mov_b32_e32 v53, 0
	v_mov_b32_e32 v54, 0
	v_mov_b32_e32 v55, 0
	v_mov_b32_e32 v56, 0
	v_mov_b32_e32 v57, 0
	v_mov_b32_e32 v58, 0
	v_mov_b32_e32 v59, 0
	v_mov_b32_e32 v60, 0
	v_mov_b32_e32 v61, 0
	v_mov_b32_e32 v62, 0
	v_mov_b32_e32 v63, 0
	v_mov_b32_e32 v64, 0
	v_mov_b32_e32 v65, 0
	v_mov_b32_e32 v218, 0
	v_mov_b32_e32 v146, 0
	v_mov_b32_e32 v154, 0x3f803f80
	v_mov_b32_e32 v147, 0
	v_mov_b32_e32 v155, 0x3f803f80
	v_mov_b32_e32 v148, 0
	v_mov_b32_e32 v156, 0x3f803f80
	v_mov_b32_e32 v149, 0
	v_mov_b32_e32 v157, 0x3f803f80
	v_mov_b32_e32 v208, 0xc1700000
	v_mov_b32_e32 v209, 0xc1700000
	v_mov_b32_e32 v210, 0xc1700000
	v_mov_b32_e32 v211, 0xc1700000
	v_mov_b32_e32 v219, 0
	v_mov_b32_e32 v150, 0
	v_mov_b32_e32 v154, 0x3f803f80
	v_mov_b32_e32 v151, 0
	v_mov_b32_e32 v155, 0x3f803f80
	v_mov_b32_e32 v152, 0
	v_mov_b32_e32 v156, 0x3f803f80
	v_mov_b32_e32 v153, 0
	v_mov_b32_e32 v157, 0x3f803f80
	v_mov_b32_e32 v212, 0xc1700000
	v_mov_b32_e32 v213, 0xc1700000
	v_mov_b32_e32 v214, 0xc1700000
	v_mov_b32_e32 v215, 0xc1700000
	s_mov_b32 s41, 0
	s_mov_b32 s42, 0
	s_waitcnt vmcnt(0)
	s_barrier

; __device__ __forceinline__ int crow(int r, int hi) { return (r & 3) + 8 * (r >> 2) + 4 * hi; }
; __device__ __forceinline__ void partialSM_pre(f32x16& p0, f32x16& p1, float& m_reg, float& alpha) {
;     constexpr float THR2 = THR * 1.4426950408889634f;
;     float pmax = p0[0];
; #pragma unroll
;     for (int r = 1; r < 16; ++r) pmax = fmaxf(pmax, p0[r]);
; #pragma unroll
;     for (int r = 0; r < 16; ++r) pmax = fmaxf(pmax, p1[r]);
;     { auto rr = __builtin_amdgcn_permlane32_swap(__float_as_uint(pmax), __float_as_uint(pmax), false, false);
;       pmax = fmaxf(__uint_as_float(rr[0]), __uint_as_float(rr[1])); }
;     if (__builtin_expect(__all(pmax <= THR2), 1)) { alpha = 1.f; }
;     else { const float d = fmaxf(pmax, 0.f); m_reg += d; alpha = __builtin_amdgcn_exp2f(-d);
; #pragma unroll
;         for (int r = 0; r < 16; ++r) { p0[r] -= d; p1[r] -= d; } }
; #pragma unroll
;     for (int r = 0; r < 16; ++r) p0[r] = __builtin_amdgcn_exp2f(p0[r]);
; }
; template <bool MLA> __device__ __forceinline__ void attn_unit(const AttnP& P, int b, int hh, int qb, LAS char* lds) {
;     ...
;             if (__any(alpha < 1.f)) { if (hi == 0) al_l[r32] = alpha; asm volatile("s_waitcnt lgkmcnt(0)" ::: "memory");
; #pragma unroll
;                 for (int d_ = 0; d_ < NCB; ++d_)
; #pragma unroll
;                     for (int r = 0; r < 16; ++r) o[d_][r] *= al_l[crow(r, hi)]; }
.Lm16_nomask_s0:
	v_max3_f32 v220, v114, v115, v116
	v_max3_f32 v220, v220, v117, v122
	v_max3_f32 v220, v220, v123, v124
	v_max3_f32 v220, v220, v125, v130
	v_max3_f32 v220, v220, v131, v132
	v_max3_f32 v220, v220, v133, v138
	v_max3_f32 v220, v220, v139, v140
	v_max_f32_e32 v220, v220, v141
	ds_bpermute_b32 v221, v246, v220
	s_waitcnt lgkmcnt(0)
	v_max_f32_e32 v220, v220, v221
	ds_bpermute_b32 v221, v247, v220
	s_waitcnt lgkmcnt(0)
	v_max_f32_e32 v220, v220, v221
	v_add_f32_e32 v220, 0x41700000, v220
	v_max_f32_e32 v221, 0, v220
	v_add_f32_e32 v218, v218, v221
	v_exp_f32_e64 v222, -v221
	v_sub_f32_e32 v114, v114, v221
	v_sub_f32_e32 v115, v115, v221
	v_sub_f32_e32 v116, v116, v221
	v_sub_f32_e32 v117, v117, v221
	v_sub_f32_e32 v122, v122, v221
	v_sub_f32_e32 v123, v123, v221
	v_sub_f32_e32 v124, v124, v221
	v_sub_f32_e32 v125, v125, v221
	v_sub_f32_e32 v130, v130, v221
	v_sub_f32_e32 v131, v131, v221
	v_sub_f32_e32 v132, v132, v221
	v_sub_f32_e32 v133, v133, v221
	v_sub_f32_e32 v138, v138, v221
	v_sub_f32_e32 v139, v139, v221
	v_sub_f32_e32 v140, v140, v221
	v_sub_f32_e32 v141, v141, v221
	v_mul_f32_e32 v146, v146, v222
	v_mul_f32_e32 v147, v147, v222
	v_mul_f32_e32 v148, v148, v222
	v_mul_f32_e32 v149, v149, v222
	v_mul_f32_e32 v2, v2, v222
	v_mul_f32_e32 v3, v3, v222
	v_mul_f32_e32 v4, v4, v222
	v_mul_f32_e32 v5, v5, v222
	v_mul_f32_e32 v10, v10, v222
	v_mul_f32_e32 v11, v11, v222
	v_mul_f32_e32 v12, v12, v222
	v_mul_f32_e32 v13, v13, v222
	v_mul_f32_e32 v18, v18, v222
	v_mul_f32_e32 v19, v19, v222
	v_mul_f32_e32 v20, v20, v222
	v_mul_f32_e32 v21, v21, v222
	v_mul_f32_e32 v26, v26, v222
	v_mul_f32_e32 v27, v27, v222
	v_mul_f32_e32 v28, v28, v222
	v_mul_f32_e32 v29, v29, v222
	v_mul_f32_e32 v34, v34, v222
	v_mul_f32_e32 v35, v35, v222
	v_mul_f32_e32 v36, v36, v222
	v_mul_f32_e32 v37, v37, v222
	v_mul_f32_e32 v42, v42, v222
	v_mul_f32_e32 v43, v43, v222
	v_mul_f32_e32 v44, v44, v222
	v_mul_f32_e32 v45, v45, v222
	v_mul_f32_e32 v50, v50, v222
	v_mul_f32_e32 v51, v51, v222
	v_mul_f32_e32 v52, v52, v222
	v_mul_f32_e32 v53, v53, v222
	v_mul_f32_e32 v58, v58, v222
	v_mul_f32_e32 v59, v59, v222
	v_mul_f32_e32 v60, v60, v222
	v_mul_f32_e32 v61, v61, v222
	v_sub_f32_e32 v208, 0xc1700000, v218
	v_sub_f32_e32 v209, 0xc1700000, v218
	v_sub_f32_e32 v210, 0xc1700000, v218
	v_sub_f32_e32 v211, 0xc1700000, v218
	v_max3_f32 v220, v118, v119, v120
	v_max3_f32 v220, v220, v121, v126
	v_max3_f32 v220, v220, v127, v128
	v_max3_f32 v220, v220, v129, v134
	v_max3_f32 v220, v220, v135, v136
	v_max3_f32 v220, v220, v137, v142
	v_max3_f32 v220, v220, v143, v144
	v_max_f32_e32 v220, v220, v145
	ds_bpermute_b32 v221, v246, v220
	s_waitcnt lgkmcnt(0)
	v_max_f32_e32 v220, v220, v221
	ds_bpermute_b32 v221, v247, v220
	s_waitcnt lgkmcnt(0)
	v_max_f32_e32 v220, v220, v221
	v_add_f32_e32 v220, 0x41700000, v220
	v_max_f32_e32 v221, 0, v220
	v_add_f32_e32 v219, v219, v221
	v_exp_f32_e64 v222, -v221
	v_sub_f32_e32 v118, v118, v221
	v_sub_f32_e32 v119, v119, v221
	v_sub_f32_e32 v120, v120, v221
	v_sub_f32_e32 v121, v121, v221
	v_sub_f32_e32 v126, v126, v221
	v_sub_f32_e32 v127, v127, v221
	v_sub_f32_e32 v128, v128, v221
	v_sub_f32_e32 v129, v129, v221
	v_sub_f32_e32 v134, v134, v221
	v_sub_f32_e32 v135, v135, v221
	v_sub_f32_e32 v136, v136, v221
	v_sub_f32_e32 v137, v137, v221
	v_sub_f32_e32 v142, v142, v221
	v_sub_f32_e32 v143, v143, v221
	v_sub_f32_e32 v144, v144, v221
	v_sub_f32_e32 v145, v145, v221
	v_mul_f32_e32 v150, v150, v222
	v_mul_f32_e32 v151, v151, v222
	v_mul_f32_e32 v152, v152, v222
	v_mul_f32_e32 v153, v153, v222
	v_mul_f32_e32 v6, v6, v222
	v_mul_f32_e32 v7, v7, v222
	v_mul_f32_e32 v8, v8, v222
	v_mul_f32_e32 v9, v9, v222
	v_mul_f32_e32 v14, v14, v222
	v_mul_f32_e32 v15, v15, v222
	v_mul_f32_e32 v16, v16, v222
	v_mul_f32_e32 v17, v17, v222
	v_mul_f32_e32 v22, v22, v222
	v_mul_f32_e32 v23, v23, v222
	v_mul_f32_e32 v24, v24, v222
	v_mul_f32_e32 v25, v25, v222
	v_mul_f32_e32 v30, v30, v222
	v_mul_f32_e32 v31, v31, v222
	v_mul_f32_e32 v32, v32, v222
	v_mul_f32_e32 v33, v33, v222
	v_mul_f32_e32 v38, v38, v222
	v_mul_f32_e32 v39, v39, v222
	v_mul_f32_e32 v40, v40, v222
	v_mul_f32_e32 v41, v41, v222
	v_mul_f32_e32 v46, v46, v222
	v_mul_f32_e32 v47, v47, v222
	v_mul_f32_e32 v48, v48, v222
	v_mul_f32_e32 v49, v49, v222
	v_mul_f32_e32 v54, v54, v222
	v_mul_f32_e32 v55, v55, v222
	v_mul_f32_e32 v56, v56, v222
	v_mul_f32_e32 v57, v57, v222
	v_mul_f32_e32 v62, v62, v222
	v_mul_f32_e32 v63, v63, v222
	v_mul_f32_e32 v64, v64, v222
	v_mul_f32_e32 v65, v65, v222
	v_sub_f32_e32 v212, 0xc1700000, v219
	v_sub_f32_e32 v213, 0xc1700000, v219
	v_sub_f32_e32 v214, 0xc1700000, v219
	v_sub_f32_e32 v215, 0xc1700000, v219
	v_exp_f32_e32 v114, v114
	v_exp_f32_e32 v115, v115
	v_exp_f32_e32 v116, v116
	v_exp_f32_e32 v117, v117
	v_exp_f32_e32 v118, v118
	v_exp_f32_e32 v119, v119
	v_exp_f32_e32 v120, v120
	v_exp_f32_e32 v121, v121
	v_exp_f32_e32 v122, v122
	v_exp_f32_e32 v123, v123
	v_exp_f32_e32 v124, v124
	v_exp_f32_e32 v125, v125
	v_exp_f32_e32 v126, v126
	v_exp_f32_e32 v127, v127
	v_exp_f32_e32 v128, v128
	v_exp_f32_e32 v129, v129
	v_exp_f32_e32 v130, v130
	v_exp_f32_e32 v131, v131
	v_exp_f32_e32 v132, v132
	v_exp_f32_e32 v133, v133
	v_exp_f32_e32 v134, v134
	v_exp_f32_e32 v135, v135
	v_exp_f32_e32 v136, v136
	v_exp_f32_e32 v137, v137
	v_exp_f32_e32 v138, v138
	v_exp_f32_e32 v139, v139
	v_exp_f32_e32 v140, v140
	v_exp_f32_e32 v141, v141
	v_exp_f32_e32 v142, v142
	v_exp_f32_e32 v143, v143
	v_exp_f32_e32 v144, v144
	v_exp_f32_e32 v145, v145
	v_cvt_pk_bf16_f32 v164, v114, v115
	v_cvt_pk_bf16_f32 v165, v116, v117
	v_cvt_pk_bf16_f32 v166, v122, v123
	v_cvt_pk_bf16_f32 v167, v124, v125
	v_cvt_pk_bf16_f32 v168, v130, v131
	v_cvt_pk_bf16_f32 v169, v132, v133
	v_cvt_pk_bf16_f32 v170, v138, v139
	v_cvt_pk_bf16_f32 v171, v140, v141
	v_cvt_pk_bf16_f32 v172, v118, v119
	v_cvt_pk_bf16_f32 v173, v120, v121
	v_cvt_pk_bf16_f32 v174, v126, v127
	v_cvt_pk_bf16_f32 v175, v128, v129
	v_cvt_pk_bf16_f32 v176, v134, v135
	v_cvt_pk_bf16_f32 v177, v136, v137
	v_cvt_pk_bf16_f32 v178, v142, v143
	v_cvt_pk_bf16_f32 v179, v144, v145
